# k25: k24 + back-edge rotation (7.11, simple form): counter/pointer/compare block moved in front of the loop-back barrier in the three GEMM K-loops
# speedup vs baseline: 1.0062x; 1.0062x over previous
; #define PG8_STAGE(bufoff, gbase, voff) do { _Pragma("unroll") for (int _i = 0; _i < 2; ++_i) \
;         __builtin_amdgcn_global_load_lds((const unsigned*)((const char*)(gbase) + (voff)[_i]), (LAS unsigned*)(lds + (bufoff) + ldsw + _i * 8192), 16, 0, 0); } while (0)
; #define PG8_LDA(dst, b, h) do { _Pragma("unroll") for (int m = 0; m < 4; ++m) _Pragma("unroll") for (int k = 0; k < 2; ++k) dst[m][k] = *(const LAS bf16x8*)(lds + PG8_SA(b, h) + aoff + m * 2048 + k * 1024); } while (0)
; #define PG8_LDB(dst, b, h) do { _Pragma("unroll") for (int n = 0; n < 2; ++n) _Pragma("unroll") for (int k = 0; k < 2; ++k) dst[n][k] = *(const LAS bf16x8*)(lds + PG8_SB(b, h) + boff + n * 2048 + k * 1024); } while (0)
; #define PG8_MMA(ai, bj, At, Bt) do { __builtin_amdgcn_s_setprio(1); _Pragma("unroll") for (int m = 0; m < 4; ++m) _Pragma("unroll") for (int n = 0; n < 2; ++n) _Pragma("unroll") for (int k = 0; k < 2; ++k) \
;         acc[ai][bj][m][n] = __builtin_amdgcn_mfma_f32_16x16x32_bf16(Bt[n][k], At[m][k], acc[ai][bj][m][n], 0, 0, 0); __builtin_amdgcn_s_setprio(0); } while (0)
; #define PG8_WAIT_V(n) asm volatile("s_waitcnt vmcnt(" #n ")" ::: "memory")
; #define PG8_WAIT_L(n) asm volatile("s_waitcnt lgkmcnt(" #n ")" ::: "memory")
; #define PG8_BAR __builtin_amdgcn_s_barrier()
; template <class Epi, int K, int lda, class Sched = StaticOrder, bool ALIGN_EPI = true>
; __device__ __forceinline__ void gemm_phase(LAS unsigned char* lds, const Gemm g, const Sched& S, const Epi& E) {
;     ...
;         for (int t = 0; t < nt; t += 2) {
;             const bool last = (t == nt - 2);
;             const char* a1 = cA + (size_t)(t + 1) * kstep;
;             const char* a2 = last ? nA : cA + (size_t)(t + 2) * kstep; const char* b2 = last ? nB : cB + (size_t)(t + 2) * kstep;
;             const char* a3 = a2 + kstep; const char* b3 = b2 + kstep;
;             PG8_LDB(B0, 0, 0); PG8_LDB(B1, 0, 1); PG8_SCHED; PG8_LDA(At, 0, 0); PG8_STAGE(PG8_SA(1, 1), a1 + hstepA, voffA);
;             PG8_WAIT_V(8); PG8_WAIT_L(0); PG8_BAR; PG8_MMA(0, 0, At, B0); PG8_MMA(0, 1, At, B1); PG8_BAR; PG8_SCHED;
;             PG8_LDA(At, 0, 1); PG8_STAGE(PG8_SB(0, 0), b2, voffB); PG8_STAGE(PG8_SB(0, 1), b2 + hstepB, voffB); PG8_STAGE(PG8_SA(0, 0), a2, voffA);
;             PG8_WAIT_V(8); PG8_WAIT_L(0); PG8_BAR; PG8_MMA(1, 0, At, B0); PG8_MMA(1, 1, At, B1); PG8_BAR; PG8_SCHED;
.LBB0_72:
	s_add_u32 s26, s74, 0xfff80080
	s_addc_u32 s27, s75, -1
	s_add_i32 s28, 0, 0x10000
	s_cmp_eq_u32 s25, 28
	s_cselect_b32 s79, s47, s27
	s_cselect_b32 s78, s53, s26
	v_add_u32_e32 v144, s28, v149
	s_cselect_b32 s77, s45, s24
	s_cselect_b32 s76, vcc_lo, vcc_hi
	s_add_i32 s29, 0, 0x14000
	ds_read_b128 v[154:157], v144
	ds_read_b128 v[158:161], v144 offset:1024
	ds_read_b128 v[162:165], v144 offset:2048
	ds_read_b128 v[166:169], v144 offset:3072
	v_add_u32_e32 v144, s29, v149
	ds_read_b128 v[170:173], v144
	ds_read_b128 v[178:181], v144 offset:1024
	ds_read_b128 v[182:185], v144 offset:2048
	ds_read_b128 v[186:189], v144 offset:3072
	v_lshl_add_u64 v[146:147], s[74:75], 0, v[140:141]
	s_add_i32 m0, s80, 0xc000
	ds_read_b128 v[190:193], v151
	ds_read_b128 v[200:203], v151 offset:1024
	ds_read_b128 v[204:207], v151 offset:2048
	ds_read_b128 v[208:211], v151 offset:3072
	ds_read_b128 v[212:215], v151 offset:4096
	ds_read_b128 v[216:219], v151 offset:5120
	ds_read_b128 v[220:223], v151 offset:6144
	ds_read_b128 v[224:227], v151 offset:7168
	global_load_lds_dwordx4 v[146:147], off
	v_lshl_add_u64 v[146:147], s[74:75], 0, v[142:143]
	s_add_i32 m0, s80, 0xe000
	s_nop 0
	global_load_lds_dwordx4 v[146:147], off
	s_waitcnt vmcnt(8)
	s_waitcnt lgkmcnt(0)
	s_barrier
	s_setprio 1
	s_waitcnt lgkmcnt(0)
	v_mfma_f32_16x16x32_bf16 v[124:127], v[154:157], v[190:193], v[124:127]
	v_mfma_f32_16x16x32_bf16 v[120:123], v[162:165], v[190:193], v[120:123]
	v_mfma_f32_16x16x32_bf16 v[108:111], v[154:157], v[204:207], v[108:111]
	v_mfma_f32_16x16x32_bf16 v[104:107], v[162:165], v[204:207], v[104:107]
	v_mfma_f32_16x16x32_bf16 v[92:95], v[154:157], v[212:215], v[92:95]
	v_mfma_f32_16x16x32_bf16 v[88:91], v[162:165], v[212:215], v[88:91]
	v_mfma_f32_16x16x32_bf16 v[76:79], v[154:157], v[220:223], v[76:79]
	v_mfma_f32_16x16x32_bf16 v[72:75], v[162:165], v[220:223], v[72:75]
	v_mfma_f32_16x16x32_bf16 v[124:127], v[158:161], v[200:203], v[124:127]
	v_mfma_f32_16x16x32_bf16 v[120:123], v[166:169], v[200:203], v[120:123]
	v_mfma_f32_16x16x32_bf16 v[108:111], v[158:161], v[208:211], v[108:111]
	v_mfma_f32_16x16x32_bf16 v[104:107], v[166:169], v[208:211], v[104:107]
	v_mfma_f32_16x16x32_bf16 v[92:95], v[158:161], v[216:219], v[92:95]
	v_mfma_f32_16x16x32_bf16 v[88:91], v[166:169], v[216:219], v[88:91]
	v_mfma_f32_16x16x32_bf16 v[76:79], v[158:161], v[224:227], v[76:79]
	v_mfma_f32_16x16x32_bf16 v[72:75], v[166:169], v[224:227], v[72:75]
	s_setprio 0
	s_setprio 1
	v_mfma_f32_16x16x32_bf16 v[116:119], v[170:173], v[190:193], v[116:119]
	v_mfma_f32_16x16x32_bf16 v[112:115], v[182:185], v[190:193], v[112:115]
	v_mfma_f32_16x16x32_bf16 v[100:103], v[170:173], v[204:207], v[100:103]
	v_mfma_f32_16x16x32_bf16 v[96:99], v[182:185], v[204:207], v[96:99]
	v_mfma_f32_16x16x32_bf16 v[84:87], v[170:173], v[212:215], v[84:87]
	v_mfma_f32_16x16x32_bf16 v[80:83], v[182:185], v[212:215], v[80:83]
	v_mfma_f32_16x16x32_bf16 v[68:71], v[170:173], v[220:223], v[68:71]
	v_mfma_f32_16x16x32_bf16 v[64:67], v[182:185], v[220:223], v[64:67]
	v_mfma_f32_16x16x32_bf16 v[116:119], v[178:181], v[200:203], v[116:119]
	v_mfma_f32_16x16x32_bf16 v[112:115], v[186:189], v[200:203], v[112:115]
	v_mfma_f32_16x16x32_bf16 v[100:103], v[178:181], v[208:211], v[100:103]
	v_mfma_f32_16x16x32_bf16 v[96:99], v[186:189], v[208:211], v[96:99]
	v_mfma_f32_16x16x32_bf16 v[84:87], v[178:181], v[216:219], v[84:87]
	v_mfma_f32_16x16x32_bf16 v[80:83], v[186:189], v[216:219], v[80:83]
	v_mfma_f32_16x16x32_bf16 v[68:71], v[178:181], v[224:227], v[68:71]
	v_mfma_f32_16x16x32_bf16 v[64:67], v[186:189], v[224:227], v[64:67]
	s_setprio 0
	s_barrier
	s_add_i32 s26, s28, s16
	v_lshl_add_u64 v[146:147], s[76:77], 0, v[132:133]
	s_mov_b32 m0, s26
	ds_read_b128 v[190:193], v151 offset:16384
	ds_read_b128 v[200:203], v151 offset:17408
	ds_read_b128 v[204:207], v151 offset:18432
	ds_read_b128 v[208:211], v151 offset:19456
	ds_read_b128 v[212:215], v151 offset:20480
	ds_read_b128 v[216:219], v151 offset:21504
	ds_read_b128 v[220:223], v151 offset:22528
	ds_read_b128 v[224:227], v151 offset:23552
	global_load_lds_dwordx4 v[146:147], off
	s_add_i32 m0, s26, 0x2000
	s_add_u32 s26, s76, 0x80000
	v_lshl_add_u64 v[174:175], s[76:77], 0, v[128:129]
	s_addc_u32 s27, s77, 0
	s_add_i32 s28, s29, s16
	global_load_lds_dwordx4 v[174:175], off
	v_lshl_add_u64 v[228:229], s[26:27], 0, v[132:133]
	s_mov_b32 m0, s28
	v_lshl_add_u64 v[230:231], s[78:79], 0, v[130:131]
	global_load_lds_dwordx4 v[228:229], off
	v_lshl_add_u64 v[228:229], s[26:27], 0, v[128:129]
	s_add_i32 m0, s28, 0x2000
	s_nop 0
	global_load_lds_dwordx4 v[228:229], off
	v_lshl_add_u64 v[228:229], s[78:79], 0, v[134:135]
	s_mov_b32 m0, s80
	s_nop 0
	global_load_lds_dwordx4 v[228:229], off
	s_mov_b32 m0, s81
	s_nop 0
	global_load_lds_dwordx4 v[230:231], off
	s_waitcnt vmcnt(8)
	s_waitcnt lgkmcnt(0)
	s_barrier
; #define PG8_STAGE(bufoff, gbase, voff) do { _Pragma("unroll") for (int _i = 0; _i < 2; ++_i) \
;         __builtin_amdgcn_global_load_lds((const unsigned*)((const char*)(gbase) + (voff)[_i]), (LAS unsigned*)(lds + (bufoff) + ldsw + _i * 8192), 16, 0, 0); } while (0)
; #define PG8_LDA(dst, b, h) do { _Pragma("unroll") for (int m = 0; m < 4; ++m) _Pragma("unroll") for (int k = 0; k < 2; ++k) dst[m][k] = *(const LAS bf16x8*)(lds + PG8_SA(b, h) + aoff + m * 2048 + k * 1024); } while (0)
; #define PG8_LDB(dst, b, h) do { _Pragma("unroll") for (int n = 0; n < 2; ++n) _Pragma("unroll") for (int k = 0; k < 2; ++k) dst[n][k] = *(const LAS bf16x8*)(lds + PG8_SB(b, h) + boff + n * 2048 + k * 1024); } while (0)
; #define PG8_MMA(ai, bj, At, Bt) do { __builtin_amdgcn_s_setprio(1); _Pragma("unroll") for (int m = 0; m < 4; ++m) _Pragma("unroll") for (int n = 0; n < 2; ++n) _Pragma("unroll") for (int k = 0; k < 2; ++k) \
;         acc[ai][bj][m][n] = __builtin_amdgcn_mfma_f32_16x16x32_bf16(Bt[n][k], At[m][k], acc[ai][bj][m][n], 0, 0, 0); __builtin_amdgcn_s_setprio(0); } while (0)
; #define PG8_WAIT_V(n) asm volatile("s_waitcnt vmcnt(" #n ")" ::: "memory")
; #define PG8_WAIT_L(n) asm volatile("s_waitcnt lgkmcnt(" #n ")" ::: "memory")
; #define PG8_BAR __builtin_amdgcn_s_barrier()
; #define PG8_SCHED __builtin_amdgcn_sched_barrier(0)
; template <class Epi, int K, int lda, class Sched = StaticOrder, bool ALIGN_EPI = true>
; __device__ __forceinline__ void gemm_phase(LAS unsigned char* lds, const Gemm g, const Sched& S, const Epi& E) {
;     ...
;             PG8_WAIT_V(8); PG8_WAIT_L(0); PG8_BAR; PG8_MMA(0, 0, At, B0); PG8_MMA(0, 1, At, B1); PG8_BAR; PG8_SCHED;
;             PG8_LDA(At, 0, 1); PG8_STAGE(PG8_SB(0, 0), b2, voffB); PG8_STAGE(PG8_SB(0, 1), b2 + hstepB, voffB); PG8_STAGE(PG8_SA(0, 0), a2, voffA);
;             PG8_WAIT_V(8); PG8_WAIT_L(0); PG8_BAR; PG8_MMA(1, 0, At, B0); PG8_MMA(1, 1, At, B1); PG8_BAR; PG8_SCHED;
;             PG8_LDB(B0, 1, 0); PG8_LDB(B1, 1, 1); PG8_SCHED; PG8_LDA(At, 1, 0); PG8_STAGE(PG8_SA(0, 1), a2 + hstepA, voffA);
;             PG8_WAIT_V(8); PG8_WAIT_L(0); PG8_BAR; PG8_MMA(0, 0, At, B0); PG8_MMA(0, 1, At, B1); PG8_BAR; PG8_SCHED;
	s_setprio 1
	s_waitcnt lgkmcnt(0)
	v_mfma_f32_16x16x32_bf16 v[60:63], v[154:157], v[190:193], v[60:63]
	v_mfma_f32_16x16x32_bf16 v[56:59], v[162:165], v[190:193], v[56:59]
	v_mfma_f32_16x16x32_bf16 v[44:47], v[154:157], v[204:207], v[44:47]
	v_mfma_f32_16x16x32_bf16 v[40:43], v[162:165], v[204:207], v[40:43]
	v_mfma_f32_16x16x32_bf16 v[28:31], v[154:157], v[212:215], v[28:31]
	v_mfma_f32_16x16x32_bf16 v[24:27], v[162:165], v[212:215], v[24:27]
	v_mfma_f32_16x16x32_bf16 v[12:15], v[154:157], v[220:223], v[12:15]
	v_mfma_f32_16x16x32_bf16 v[8:11], v[162:165], v[220:223], v[8:11]
	v_mfma_f32_16x16x32_bf16 v[60:63], v[158:161], v[200:203], v[60:63]
	v_mfma_f32_16x16x32_bf16 v[56:59], v[166:169], v[200:203], v[56:59]
	v_mfma_f32_16x16x32_bf16 v[44:47], v[158:161], v[208:211], v[44:47]
	v_mfma_f32_16x16x32_bf16 v[40:43], v[166:169], v[208:211], v[40:43]
	v_mfma_f32_16x16x32_bf16 v[28:31], v[158:161], v[216:219], v[28:31]
	v_mfma_f32_16x16x32_bf16 v[24:27], v[166:169], v[216:219], v[24:27]
	v_mfma_f32_16x16x32_bf16 v[12:15], v[158:161], v[224:227], v[12:15]
	v_mfma_f32_16x16x32_bf16 v[8:11], v[166:169], v[224:227], v[8:11]
	s_setprio 0
	s_setprio 1
	v_mfma_f32_16x16x32_bf16 v[52:55], v[170:173], v[190:193], v[52:55]
	v_mfma_f32_16x16x32_bf16 v[48:51], v[182:185], v[190:193], v[48:51]
	v_mfma_f32_16x16x32_bf16 v[36:39], v[170:173], v[204:207], v[36:39]
	v_mfma_f32_16x16x32_bf16 v[32:35], v[182:185], v[204:207], v[32:35]
	v_mfma_f32_16x16x32_bf16 v[20:23], v[170:173], v[212:215], v[20:23]
	v_mfma_f32_16x16x32_bf16 v[16:19], v[182:185], v[212:215], v[16:19]
	v_mfma_f32_16x16x32_bf16 v[4:7], v[170:173], v[220:223], v[4:7]
	v_mfma_f32_16x16x32_bf16 v[0:3], v[182:185], v[220:223], v[0:3]
	v_mfma_f32_16x16x32_bf16 v[52:55], v[178:181], v[200:203], v[52:55]
	v_mfma_f32_16x16x32_bf16 v[48:51], v[186:189], v[200:203], v[48:51]
	v_mfma_f32_16x16x32_bf16 v[36:39], v[178:181], v[208:211], v[36:39]
	v_mfma_f32_16x16x32_bf16 v[32:35], v[186:189], v[208:211], v[32:35]
	v_mfma_f32_16x16x32_bf16 v[20:23], v[178:181], v[216:219], v[20:23]
	v_mfma_f32_16x16x32_bf16 v[16:19], v[186:189], v[216:219], v[16:19]
	v_mfma_f32_16x16x32_bf16 v[4:7], v[178:181], v[224:227], v[4:7]
	v_mfma_f32_16x16x32_bf16 v[0:3], v[186:189], v[224:227], v[0:3]
	s_setprio 0
	s_barrier
	s_add_i32 s28, 0, 0x18000
	v_add_u32_e32 v144, s28, v149
	s_add_i32 s29, 0, 0x1c000
	ds_read_b128 v[154:157], v144
	ds_read_b128 v[158:161], v144 offset:1024
	ds_read_b128 v[162:165], v144 offset:2048
	ds_read_b128 v[166:169], v144 offset:3072
	v_add_u32_e32 v144, s29, v149
	ds_read_b128 v[170:173], v144
	ds_read_b128 v[178:181], v144 offset:1024
	ds_read_b128 v[182:185], v144 offset:2048
	ds_read_b128 v[186:189], v144 offset:3072
	s_add_u32 s26, s78, 0x80000
	s_addc_u32 s27, s79, 0
	s_mov_b32 m0, s82
	v_lshl_add_u64 v[232:233], s[26:27], 0, v[134:135]
	ds_read_b128 v[190:193], v151 offset:32768
	ds_read_b128 v[200:203], v151 offset:33792
	ds_read_b128 v[204:207], v151 offset:34816
	ds_read_b128 v[208:211], v151 offset:35840
	ds_read_b128 v[212:215], v151 offset:36864
	ds_read_b128 v[216:219], v151 offset:37888
	ds_read_b128 v[220:223], v151 offset:38912
	ds_read_b128 v[224:227], v151 offset:39936
	global_load_lds_dwordx4 v[232:233], off
	v_lshl_add_u64 v[232:233], s[26:27], 0, v[130:131]
	s_mov_b32 m0, s83
	s_nop 0
	global_load_lds_dwordx4 v[232:233], off
	s_waitcnt vmcnt(8)
	s_waitcnt lgkmcnt(0)
	s_barrier
	s_setprio 1
	s_waitcnt lgkmcnt(0)
	v_mfma_f32_16x16x32_bf16 v[124:127], v[154:157], v[190:193], v[124:127]
	v_mfma_f32_16x16x32_bf16 v[120:123], v[162:165], v[190:193], v[120:123]
	v_mfma_f32_16x16x32_bf16 v[108:111], v[154:157], v[204:207], v[108:111]
	v_mfma_f32_16x16x32_bf16 v[104:107], v[162:165], v[204:207], v[104:107]
	v_mfma_f32_16x16x32_bf16 v[92:95], v[154:157], v[212:215], v[92:95]
	v_mfma_f32_16x16x32_bf16 v[88:91], v[162:165], v[212:215], v[88:91]
	v_mfma_f32_16x16x32_bf16 v[76:79], v[154:157], v[220:223], v[76:79]
	v_mfma_f32_16x16x32_bf16 v[72:75], v[162:165], v[220:223], v[72:75]
	v_mfma_f32_16x16x32_bf16 v[124:127], v[158:161], v[200:203], v[124:127]
	v_mfma_f32_16x16x32_bf16 v[120:123], v[166:169], v[200:203], v[120:123]
	v_mfma_f32_16x16x32_bf16 v[108:111], v[158:161], v[208:211], v[108:111]
	v_mfma_f32_16x16x32_bf16 v[104:107], v[166:169], v[208:211], v[104:107]
	v_mfma_f32_16x16x32_bf16 v[92:95], v[158:161], v[216:219], v[92:95]
	v_mfma_f32_16x16x32_bf16 v[88:91], v[166:169], v[216:219], v[88:91]
	v_mfma_f32_16x16x32_bf16 v[76:79], v[158:161], v[224:227], v[76:79]
	v_mfma_f32_16x16x32_bf16 v[72:75], v[166:169], v[224:227], v[72:75]
	s_setprio 0
	s_setprio 1
	v_mfma_f32_16x16x32_bf16 v[116:119], v[170:173], v[190:193], v[116:119]
	v_mfma_f32_16x16x32_bf16 v[112:115], v[182:185], v[190:193], v[112:115]
	v_mfma_f32_16x16x32_bf16 v[100:103], v[170:173], v[204:207], v[100:103]
	v_mfma_f32_16x16x32_bf16 v[96:99], v[182:185], v[204:207], v[96:99]
	v_mfma_f32_16x16x32_bf16 v[84:87], v[170:173], v[212:215], v[84:87]
	v_mfma_f32_16x16x32_bf16 v[80:83], v[182:185], v[212:215], v[80:83]
	v_mfma_f32_16x16x32_bf16 v[68:71], v[170:173], v[220:223], v[68:71]
	v_mfma_f32_16x16x32_bf16 v[64:67], v[182:185], v[220:223], v[64:67]
	v_mfma_f32_16x16x32_bf16 v[116:119], v[178:181], v[200:203], v[116:119]
	v_mfma_f32_16x16x32_bf16 v[112:115], v[186:189], v[200:203], v[112:115]
	v_mfma_f32_16x16x32_bf16 v[100:103], v[178:181], v[208:211], v[100:103]
	v_mfma_f32_16x16x32_bf16 v[96:99], v[186:189], v[208:211], v[96:99]
	v_mfma_f32_16x16x32_bf16 v[84:87], v[178:181], v[216:219], v[84:87]
	v_mfma_f32_16x16x32_bf16 v[80:83], v[186:189], v[216:219], v[80:83]
	v_mfma_f32_16x16x32_bf16 v[68:71], v[178:181], v[224:227], v[68:71]
	v_mfma_f32_16x16x32_bf16 v[64:67], v[186:189], v[224:227], v[64:67]
	s_setprio 0
	s_barrier
; #define PG8_STAGE(bufoff, gbase, voff) do { _Pragma("unroll") for (int _i = 0; _i < 2; ++_i) \
;         __builtin_amdgcn_global_load_lds((const unsigned*)((const char*)(gbase) + (voff)[_i]), (LAS unsigned*)(lds + (bufoff) + ldsw + _i * 8192), 16, 0, 0); } while (0)
; #define PG8_LDA(dst, b, h) do { _Pragma("unroll") for (int m = 0; m < 4; ++m) _Pragma("unroll") for (int k = 0; k < 2; ++k) dst[m][k] = *(const LAS bf16x8*)(lds + PG8_SA(b, h) + aoff + m * 2048 + k * 1024); } while (0)
; #define PG8_LDB(dst, b, h) do { _Pragma("unroll") for (int n = 0; n < 2; ++n) _Pragma("unroll") for (int k = 0; k < 2; ++k) dst[n][k] = *(const LAS bf16x8*)(lds + PG8_SB(b, h) + boff + n * 2048 + k * 1024); } while (0)
; #define PG8_MMA(ai, bj, At, Bt) do { __builtin_amdgcn_s_setprio(1); _Pragma("unroll") for (int m = 0; m < 4; ++m) _Pragma("unroll") for (int n = 0; n < 2; ++n) _Pragma("unroll") for (int k = 0; k < 2; ++k) \
;         acc[ai][bj][m][n] = __builtin_amdgcn_mfma_f32_16x16x32_bf16(Bt[n][k], At[m][k], acc[ai][bj][m][n], 0, 0, 0); __builtin_amdgcn_s_setprio(0); } while (0)
; #define PG8_WAIT_V(n) asm volatile("s_waitcnt vmcnt(" #n ")" ::: "memory")
; #define PG8_WAIT_L(n) asm volatile("s_waitcnt lgkmcnt(" #n ")" ::: "memory")
; #define PG8_BAR __builtin_amdgcn_s_barrier()
; #define PG8_SCHED __builtin_amdgcn_sched_barrier(0)
; template <class Epi, int K, int lda, class Sched = StaticOrder, bool ALIGN_EPI = true>
; __device__ __forceinline__ void gemm_phase(LAS unsigned char* lds, const Gemm g, const Sched& S, const Epi& E) {
;     ...
;             PG8_LDB(B0, 1, 0); PG8_LDB(B1, 1, 1); PG8_SCHED; PG8_LDA(At, 1, 0); PG8_STAGE(PG8_SA(0, 1), a2 + hstepA, voffA);
;             PG8_WAIT_V(8); PG8_WAIT_L(0); PG8_BAR; PG8_MMA(0, 0, At, B0); PG8_MMA(0, 1, At, B1); PG8_BAR; PG8_SCHED;
;             PG8_LDA(At, 1, 1); PG8_STAGE(PG8_SB(1, 0), b3, voffB); PG8_STAGE(PG8_SB(1, 1), b3 + hstepB, voffB); PG8_STAGE(PG8_SA(1, 0), a3, voffA);
;             PG8_WAIT_V(8); PG8_WAIT_L(0); PG8_BAR; PG8_MMA(1, 0, At, B0); PG8_MMA(1, 1, At, B1); PG8_BAR; PG8_SCHED;
;         }
	s_add_i32 s26, s28, s16
	v_lshl_add_u64 v[146:147], v[146:147], 0, s[66:67]
	s_mov_b32 m0, s26
	ds_read_b128 v[190:193], v151 offset:49152
	ds_read_b128 v[200:203], v151 offset:50176
	ds_read_b128 v[204:207], v151 offset:51200
	ds_read_b128 v[208:211], v151 offset:52224
	ds_read_b128 v[212:215], v151 offset:53248
	ds_read_b128 v[216:219], v151 offset:54272
	ds_read_b128 v[220:223], v151 offset:55296
	ds_read_b128 v[224:227], v151 offset:56320
	global_load_lds_dwordx4 v[146:147], off
	s_add_i32 m0, s26, 0x2000
	s_add_u32 s26, s76, 0x80080
	v_lshl_add_u64 v[146:147], v[174:175], 0, s[66:67]
	s_addc_u32 s27, s77, 0
	s_add_i32 s28, s29, s16
	global_load_lds_dwordx4 v[146:147], off
	v_lshl_add_u64 v[146:147], s[26:27], 0, v[132:133]
	s_mov_b32 m0, s28
	s_nop 0
	global_load_lds_dwordx4 v[146:147], off
	v_lshl_add_u64 v[146:147], s[26:27], 0, v[128:129]
	s_add_i32 m0, s28, 0x2000
	s_nop 0
	global_load_lds_dwordx4 v[146:147], off
	v_lshl_add_u64 v[146:147], v[228:229], 0, s[66:67]
	s_mov_b32 m0, s86
	s_nop 0
	global_load_lds_dwordx4 v[146:147], off
	v_lshl_add_u64 v[146:147], v[230:231], 0, s[66:67]
	s_mov_b32 m0, s87
	s_nop 0
	global_load_lds_dwordx4 v[146:147], off
	s_waitcnt vmcnt(8)
	s_waitcnt lgkmcnt(0)
	s_barrier
	s_setprio 1
	s_waitcnt lgkmcnt(0)
	v_mfma_f32_16x16x32_bf16 v[60:63], v[154:157], v[190:193], v[60:63]
	v_mfma_f32_16x16x32_bf16 v[56:59], v[162:165], v[190:193], v[56:59]
	v_mfma_f32_16x16x32_bf16 v[44:47], v[154:157], v[204:207], v[44:47]
	v_mfma_f32_16x16x32_bf16 v[40:43], v[162:165], v[204:207], v[40:43]
	v_mfma_f32_16x16x32_bf16 v[28:31], v[154:157], v[212:215], v[28:31]
	v_mfma_f32_16x16x32_bf16 v[24:27], v[162:165], v[212:215], v[24:27]
	v_mfma_f32_16x16x32_bf16 v[12:15], v[154:157], v[220:223], v[12:15]
	v_mfma_f32_16x16x32_bf16 v[8:11], v[162:165], v[220:223], v[8:11]
	v_mfma_f32_16x16x32_bf16 v[60:63], v[158:161], v[200:203], v[60:63]
	v_mfma_f32_16x16x32_bf16 v[56:59], v[166:169], v[200:203], v[56:59]
	v_mfma_f32_16x16x32_bf16 v[44:47], v[158:161], v[208:211], v[44:47]
	v_mfma_f32_16x16x32_bf16 v[40:43], v[166:169], v[208:211], v[40:43]
	v_mfma_f32_16x16x32_bf16 v[28:31], v[158:161], v[216:219], v[28:31]
	v_mfma_f32_16x16x32_bf16 v[24:27], v[166:169], v[216:219], v[24:27]
	v_mfma_f32_16x16x32_bf16 v[12:15], v[158:161], v[224:227], v[12:15]
	v_mfma_f32_16x16x32_bf16 v[8:11], v[166:169], v[224:227], v[8:11]
	s_setprio 0
	s_setprio 1
	v_mfma_f32_16x16x32_bf16 v[52:55], v[170:173], v[190:193], v[52:55]
	v_mfma_f32_16x16x32_bf16 v[48:51], v[182:185], v[190:193], v[48:51]
	v_mfma_f32_16x16x32_bf16 v[36:39], v[170:173], v[204:207], v[36:39]
	v_mfma_f32_16x16x32_bf16 v[32:35], v[182:185], v[204:207], v[32:35]
	v_mfma_f32_16x16x32_bf16 v[20:23], v[170:173], v[212:215], v[20:23]
	v_mfma_f32_16x16x32_bf16 v[16:19], v[182:185], v[212:215], v[16:19]
	v_mfma_f32_16x16x32_bf16 v[4:7], v[170:173], v[220:223], v[4:7]
	v_mfma_f32_16x16x32_bf16 v[0:3], v[182:185], v[220:223], v[0:3]
	v_mfma_f32_16x16x32_bf16 v[52:55], v[178:181], v[200:203], v[52:55]
	v_mfma_f32_16x16x32_bf16 v[48:51], v[186:189], v[200:203], v[48:51]
	v_mfma_f32_16x16x32_bf16 v[36:39], v[178:181], v[208:211], v[36:39]
	v_mfma_f32_16x16x32_bf16 v[32:35], v[186:189], v[208:211], v[32:35]
	v_mfma_f32_16x16x32_bf16 v[20:23], v[178:181], v[216:219], v[20:23]
	v_mfma_f32_16x16x32_bf16 v[16:19], v[186:189], v[216:219], v[16:19]
	v_mfma_f32_16x16x32_bf16 v[4:7], v[178:181], v[224:227], v[4:7]
	v_mfma_f32_16x16x32_bf16 v[0:3], v[186:189], v[224:227], v[0:3]
	s_setprio 0
	s_add_i32 s25, s25, 2
	s_add_u32 s74, s74, 0x100
	s_addc_u32 s75, s75, 0
	s_add_u32 vcc_hi, vcc_hi, 0x100
	s_addc_u32 s24, s24, 0
	s_cmp_gt_u32 s25, 29
	s_barrier
	s_cbranch_scc0 .LBB0_72
	s_and_b64 vcc, exec, s[42:43]
	s_cbranch_vccz .LBB0_75
	s_barrier

; #define PG8_STAGE(bufoff, gbase, voff) do { _Pragma("unroll") for (int _i = 0; _i < 2; ++_i) \
;         __builtin_amdgcn_global_load_lds((const unsigned*)((const char*)(gbase) + (voff)[_i]), (LAS unsigned*)(lds + (bufoff) + ldsw + _i * 8192), 16, 0, 0); } while (0)
; #define PG8_LDA(dst, b, h) do { _Pragma("unroll") for (int m = 0; m < 4; ++m) _Pragma("unroll") for (int k = 0; k < 2; ++k) dst[m][k] = *(const LAS bf16x8*)(lds + PG8_SA(b, h) + aoff + m * 2048 + k * 1024); } while (0)
; #define PG8_LDB(dst, b, h) do { _Pragma("unroll") for (int n = 0; n < 2; ++n) _Pragma("unroll") for (int k = 0; k < 2; ++k) dst[n][k] = *(const LAS bf16x8*)(lds + PG8_SB(b, h) + boff + n * 2048 + k * 1024); } while (0)
; #define PG8_MMA(ai, bj, At, Bt) do { __builtin_amdgcn_s_setprio(1); _Pragma("unroll") for (int m = 0; m < 4; ++m) _Pragma("unroll") for (int n = 0; n < 2; ++n) _Pragma("unroll") for (int k = 0; k < 2; ++k) \
;         acc[ai][bj][m][n] = __builtin_amdgcn_mfma_f32_16x16x32_bf16(Bt[n][k], At[m][k], acc[ai][bj][m][n], 0, 0, 0); __builtin_amdgcn_s_setprio(0); } while (0)
; #define PG8_WAIT_V(n) asm volatile("s_waitcnt vmcnt(" #n ")" ::: "memory")
; #define PG8_WAIT_L(n) asm volatile("s_waitcnt lgkmcnt(" #n ")" ::: "memory")
; #define PG8_BAR __builtin_amdgcn_s_barrier()
; template <class Epi, int K, int lda, class Sched = StaticOrder, bool ALIGN_EPI = true>
; __device__ __forceinline__ void gemm_phase(LAS unsigned char* lds, const Gemm g, const Sched& S, const Epi& E) {
;     ...
;         for (int t = 0; t < nt; t += 2) {
;             const bool last = (t == nt - 2);
;             const char* a1 = cA + (size_t)(t + 1) * kstep;
;             const char* a2 = last ? nA : cA + (size_t)(t + 2) * kstep; const char* b2 = last ? nB : cB + (size_t)(t + 2) * kstep;
;             const char* a3 = a2 + kstep; const char* b3 = b2 + kstep;
;             PG8_LDB(B0, 0, 0); PG8_LDB(B1, 0, 1); PG8_SCHED; PG8_LDA(At, 0, 0); PG8_STAGE(PG8_SA(1, 1), a1 + hstepA, voffA);
;             PG8_WAIT_V(8); PG8_WAIT_L(0); PG8_BAR; PG8_MMA(0, 0, At, B0); PG8_MMA(0, 1, At, B1); PG8_BAR; PG8_SCHED;
;             PG8_LDA(At, 0, 1); PG8_STAGE(PG8_SB(0, 0), b2, voffB); PG8_STAGE(PG8_SB(0, 1), b2 + hstepB, voffB); PG8_STAGE(PG8_SA(0, 0), a2, voffA);
;             PG8_WAIT_V(8); PG8_WAIT_L(0); PG8_BAR; PG8_MMA(1, 0, At, B0); PG8_MMA(1, 1, At, B1); PG8_BAR; PG8_SCHED;
.LBB0_366:
	s_add_u32 s80, s40, 0x100
	s_addc_u32 s81, s41, 0
	s_add_i32 s23, 0, 0x10000
	s_cmp_eq_u32 s22, 60
	s_cselect_b32 s85, s77, s81
	s_cselect_b32 s84, s76, s80
	v_add_u32_e32 v150, s23, v161
	s_cselect_b32 s83, s49, s79
	s_cselect_b32 s82, s48, s78
	s_add_i32 s26, 0, 0x14000
	ds_read_b128 v[146:149], v150
	ds_read_b128 v[172:175], v150 offset:1024
	ds_read_b128 v[178:181], v150 offset:2048
	ds_read_b128 v[182:185], v150 offset:3072
	v_add_u32_e32 v150, s26, v161
	ds_read_b128 v[186:189], v150
	ds_read_b128 v[190:193], v150 offset:1024
	ds_read_b128 v[200:203], v150 offset:2048
	ds_read_b128 v[204:207], v150 offset:3072
	v_lshl_add_u64 v[150:151], s[40:41], 0, v[142:143]
	s_add_i32 m0, s14, 0xc000
	ds_read_b128 v[208:211], v170
	ds_read_b128 v[212:215], v170 offset:1024
	ds_read_b128 v[216:219], v170 offset:2048
	ds_read_b128 v[220:223], v170 offset:3072
	ds_read_b128 v[224:227], v170 offset:4096
	ds_read_b128 v[228:231], v170 offset:5120
	ds_read_b128 v[232:235], v170 offset:6144
	ds_read_b128 v[236:239], v170 offset:7168
	global_load_lds_dwordx4 v[150:151], off
	v_lshl_add_u64 v[150:151], s[40:41], 0, v[144:145]
	s_add_i32 m0, s14, 0xe000
	s_nop 0
	global_load_lds_dwordx4 v[150:151], off
	s_waitcnt vmcnt(8)
	s_waitcnt lgkmcnt(0)
	s_barrier
	s_setprio 1
	s_waitcnt lgkmcnt(0)
	v_mfma_f32_16x16x32_bf16 v[124:127], v[146:149], v[208:211], v[124:127]
	v_mfma_f32_16x16x32_bf16 v[120:123], v[178:181], v[208:211], v[120:123]
	v_mfma_f32_16x16x32_bf16 v[108:111], v[146:149], v[216:219], v[108:111]
	v_mfma_f32_16x16x32_bf16 v[104:107], v[178:181], v[216:219], v[104:107]
	v_mfma_f32_16x16x32_bf16 v[92:95], v[146:149], v[224:227], v[92:95]
	v_mfma_f32_16x16x32_bf16 v[88:91], v[178:181], v[224:227], v[88:91]
	v_mfma_f32_16x16x32_bf16 v[76:79], v[146:149], v[232:235], v[76:79]
	v_mfma_f32_16x16x32_bf16 v[72:75], v[178:181], v[232:235], v[72:75]
	v_mfma_f32_16x16x32_bf16 v[124:127], v[172:175], v[212:215], v[124:127]
	v_mfma_f32_16x16x32_bf16 v[120:123], v[182:185], v[212:215], v[120:123]
	v_mfma_f32_16x16x32_bf16 v[108:111], v[172:175], v[220:223], v[108:111]
	v_mfma_f32_16x16x32_bf16 v[104:107], v[182:185], v[220:223], v[104:107]
	v_mfma_f32_16x16x32_bf16 v[92:95], v[172:175], v[228:231], v[92:95]
	v_mfma_f32_16x16x32_bf16 v[88:91], v[182:185], v[228:231], v[88:91]
	v_mfma_f32_16x16x32_bf16 v[76:79], v[172:175], v[236:239], v[76:79]
	v_mfma_f32_16x16x32_bf16 v[72:75], v[182:185], v[236:239], v[72:75]
	s_setprio 0
	s_setprio 1
	v_mfma_f32_16x16x32_bf16 v[116:119], v[186:189], v[208:211], v[116:119]
	v_mfma_f32_16x16x32_bf16 v[112:115], v[200:203], v[208:211], v[112:115]
	v_mfma_f32_16x16x32_bf16 v[100:103], v[186:189], v[216:219], v[100:103]
	v_mfma_f32_16x16x32_bf16 v[96:99], v[200:203], v[216:219], v[96:99]
	v_mfma_f32_16x16x32_bf16 v[84:87], v[186:189], v[224:227], v[84:87]
	v_mfma_f32_16x16x32_bf16 v[80:83], v[200:203], v[224:227], v[80:83]
	v_mfma_f32_16x16x32_bf16 v[68:71], v[186:189], v[232:235], v[68:71]
	v_mfma_f32_16x16x32_bf16 v[64:67], v[200:203], v[232:235], v[64:67]
	v_mfma_f32_16x16x32_bf16 v[116:119], v[190:193], v[212:215], v[116:119]
	v_mfma_f32_16x16x32_bf16 v[112:115], v[204:207], v[212:215], v[112:115]
	v_mfma_f32_16x16x32_bf16 v[100:103], v[190:193], v[220:223], v[100:103]
	v_mfma_f32_16x16x32_bf16 v[96:99], v[204:207], v[220:223], v[96:99]
	v_mfma_f32_16x16x32_bf16 v[84:87], v[190:193], v[228:231], v[84:87]
	v_mfma_f32_16x16x32_bf16 v[80:83], v[204:207], v[228:231], v[80:83]
	v_mfma_f32_16x16x32_bf16 v[68:71], v[190:193], v[236:239], v[68:71]
	v_mfma_f32_16x16x32_bf16 v[64:67], v[204:207], v[236:239], v[64:67]
	s_setprio 0
	s_barrier
	s_add_i32 s23, s23, s87
	v_lshl_add_u64 v[150:151], s[82:83], 0, v[130:131]
	s_mov_b32 m0, s23
	ds_read_b128 v[208:211], v170 offset:16384
	ds_read_b128 v[212:215], v170 offset:17408
	ds_read_b128 v[216:219], v170 offset:18432
	ds_read_b128 v[220:223], v170 offset:19456
	ds_read_b128 v[224:227], v170 offset:20480
	ds_read_b128 v[228:231], v170 offset:21504
	ds_read_b128 v[232:235], v170 offset:22528
	ds_read_b128 v[236:239], v170 offset:23552
	global_load_lds_dwordx4 v[150:151], off
	s_add_i32 m0, s23, 0x2000
	s_add_u32 s24, s82, 0x100000
	v_lshl_add_u64 v[194:195], s[82:83], 0, v[134:135]
	s_addc_u32 s25, s83, 0
	s_add_i32 s23, s26, s87
	global_load_lds_dwordx4 v[194:195], off
	v_lshl_add_u64 v[196:197], s[24:25], 0, v[130:131]
	s_mov_b32 m0, s23
	v_lshl_add_u64 v[240:241], s[84:85], 0, v[132:133]
	global_load_lds_dwordx4 v[196:197], off
	v_lshl_add_u64 v[196:197], s[24:25], 0, v[134:135]
	s_add_i32 m0, s23, 0x2000
	s_nop 0
	global_load_lds_dwordx4 v[196:197], off
	v_lshl_add_u64 v[196:197], s[84:85], 0, v[128:129]
	s_mov_b32 m0, s14
	s_nop 0
	global_load_lds_dwordx4 v[196:197], off
	s_mov_b32 m0, s15
	s_nop 0
	global_load_lds_dwordx4 v[240:241], off
	s_waitcnt vmcnt(8)
	s_waitcnt lgkmcnt(0)
	s_barrier
; #define PG8_STAGE(bufoff, gbase, voff) do { _Pragma("unroll") for (int _i = 0; _i < 2; ++_i) \
;         __builtin_amdgcn_global_load_lds((const unsigned*)((const char*)(gbase) + (voff)[_i]), (LAS unsigned*)(lds + (bufoff) + ldsw + _i * 8192), 16, 0, 0); } while (0)
; #define PG8_LDA(dst, b, h) do { _Pragma("unroll") for (int m = 0; m < 4; ++m) _Pragma("unroll") for (int k = 0; k < 2; ++k) dst[m][k] = *(const LAS bf16x8*)(lds + PG8_SA(b, h) + aoff + m * 2048 + k * 1024); } while (0)
; #define PG8_LDB(dst, b, h) do { _Pragma("unroll") for (int n = 0; n < 2; ++n) _Pragma("unroll") for (int k = 0; k < 2; ++k) dst[n][k] = *(const LAS bf16x8*)(lds + PG8_SB(b, h) + boff + n * 2048 + k * 1024); } while (0)
; #define PG8_MMA(ai, bj, At, Bt) do { __builtin_amdgcn_s_setprio(1); _Pragma("unroll") for (int m = 0; m < 4; ++m) _Pragma("unroll") for (int n = 0; n < 2; ++n) _Pragma("unroll") for (int k = 0; k < 2; ++k) \
;         acc[ai][bj][m][n] = __builtin_amdgcn_mfma_f32_16x16x32_bf16(Bt[n][k], At[m][k], acc[ai][bj][m][n], 0, 0, 0); __builtin_amdgcn_s_setprio(0); } while (0)
; #define PG8_WAIT_V(n) asm volatile("s_waitcnt vmcnt(" #n ")" ::: "memory")
; #define PG8_WAIT_L(n) asm volatile("s_waitcnt lgkmcnt(" #n ")" ::: "memory")
; #define PG8_BAR __builtin_amdgcn_s_barrier()
; #define PG8_SCHED __builtin_amdgcn_sched_barrier(0)
; template <class Epi, int K, int lda, class Sched = StaticOrder, bool ALIGN_EPI = true>
; __device__ __forceinline__ void gemm_phase(LAS unsigned char* lds, const Gemm g, const Sched& S, const Epi& E) {
;     ...
;             PG8_WAIT_V(8); PG8_WAIT_L(0); PG8_BAR; PG8_MMA(0, 0, At, B0); PG8_MMA(0, 1, At, B1); PG8_BAR; PG8_SCHED;
;             PG8_LDA(At, 0, 1); PG8_STAGE(PG8_SB(0, 0), b2, voffB); PG8_STAGE(PG8_SB(0, 1), b2 + hstepB, voffB); PG8_STAGE(PG8_SA(0, 0), a2, voffA);
;             PG8_WAIT_V(8); PG8_WAIT_L(0); PG8_BAR; PG8_MMA(1, 0, At, B0); PG8_MMA(1, 1, At, B1); PG8_BAR; PG8_SCHED;
;             PG8_LDB(B0, 1, 0); PG8_LDB(B1, 1, 1); PG8_SCHED; PG8_LDA(At, 1, 0); PG8_STAGE(PG8_SA(0, 1), a2 + hstepA, voffA);
;             PG8_WAIT_V(8); PG8_WAIT_L(0); PG8_BAR; PG8_MMA(0, 0, At, B0); PG8_MMA(0, 1, At, B1); PG8_BAR; PG8_SCHED;
	s_setprio 1
	s_waitcnt lgkmcnt(0)
	v_mfma_f32_16x16x32_bf16 v[60:63], v[146:149], v[208:211], v[60:63]
	v_mfma_f32_16x16x32_bf16 v[56:59], v[178:181], v[208:211], v[56:59]
	v_mfma_f32_16x16x32_bf16 v[44:47], v[146:149], v[216:219], v[44:47]
	v_mfma_f32_16x16x32_bf16 v[40:43], v[178:181], v[216:219], v[40:43]
	v_mfma_f32_16x16x32_bf16 v[28:31], v[146:149], v[224:227], v[28:31]
	v_mfma_f32_16x16x32_bf16 v[24:27], v[178:181], v[224:227], v[24:27]
	v_mfma_f32_16x16x32_bf16 v[12:15], v[146:149], v[232:235], v[12:15]
	v_mfma_f32_16x16x32_bf16 v[8:11], v[178:181], v[232:235], v[8:11]
	v_mfma_f32_16x16x32_bf16 v[60:63], v[172:175], v[212:215], v[60:63]
	v_mfma_f32_16x16x32_bf16 v[56:59], v[182:185], v[212:215], v[56:59]
	v_mfma_f32_16x16x32_bf16 v[44:47], v[172:175], v[220:223], v[44:47]
	v_mfma_f32_16x16x32_bf16 v[40:43], v[182:185], v[220:223], v[40:43]
	v_mfma_f32_16x16x32_bf16 v[28:31], v[172:175], v[228:231], v[28:31]
	v_mfma_f32_16x16x32_bf16 v[24:27], v[182:185], v[228:231], v[24:27]
	v_mfma_f32_16x16x32_bf16 v[12:15], v[172:175], v[236:239], v[12:15]
	v_mfma_f32_16x16x32_bf16 v[8:11], v[182:185], v[236:239], v[8:11]
	s_setprio 0
	s_setprio 1
	v_mfma_f32_16x16x32_bf16 v[52:55], v[186:189], v[208:211], v[52:55]
	v_mfma_f32_16x16x32_bf16 v[48:51], v[200:203], v[208:211], v[48:51]
	v_mfma_f32_16x16x32_bf16 v[36:39], v[186:189], v[216:219], v[36:39]
	v_mfma_f32_16x16x32_bf16 v[32:35], v[200:203], v[216:219], v[32:35]
	v_mfma_f32_16x16x32_bf16 v[20:23], v[186:189], v[224:227], v[20:23]
	v_mfma_f32_16x16x32_bf16 v[16:19], v[200:203], v[224:227], v[16:19]
	v_mfma_f32_16x16x32_bf16 v[4:7], v[186:189], v[232:235], v[4:7]
	v_mfma_f32_16x16x32_bf16 v[0:3], v[200:203], v[232:235], v[0:3]
	v_mfma_f32_16x16x32_bf16 v[52:55], v[190:193], v[212:215], v[52:55]
	v_mfma_f32_16x16x32_bf16 v[48:51], v[204:207], v[212:215], v[48:51]
	v_mfma_f32_16x16x32_bf16 v[36:39], v[190:193], v[220:223], v[36:39]
	v_mfma_f32_16x16x32_bf16 v[32:35], v[204:207], v[220:223], v[32:35]
	v_mfma_f32_16x16x32_bf16 v[20:23], v[190:193], v[228:231], v[20:23]
	v_mfma_f32_16x16x32_bf16 v[16:19], v[204:207], v[228:231], v[16:19]
	v_mfma_f32_16x16x32_bf16 v[4:7], v[190:193], v[236:239], v[4:7]
	v_mfma_f32_16x16x32_bf16 v[0:3], v[204:207], v[236:239], v[0:3]
	s_setprio 0
	s_barrier
	s_add_i32 s23, 0, 0x18000
	v_add_u32_e32 v176, s23, v161
	s_add_i32 s26, 0, 0x1c000
	ds_read_b128 v[146:149], v176
	ds_read_b128 v[172:175], v176 offset:1024
	ds_read_b128 v[178:181], v176 offset:2048
	ds_read_b128 v[182:185], v176 offset:3072
	v_add_u32_e32 v176, s26, v161
	ds_read_b128 v[186:189], v176
	ds_read_b128 v[190:193], v176 offset:1024
	ds_read_b128 v[200:203], v176 offset:2048
	ds_read_b128 v[204:207], v176 offset:3072
	s_add_u32 s24, s84, 0x300000
	s_addc_u32 s25, s85, 0
	s_mov_b32 m0, s16
	v_lshl_add_u64 v[242:243], s[24:25], 0, v[128:129]
	ds_read_b128 v[208:211], v170 offset:32768
	ds_read_b128 v[212:215], v170 offset:33792
	ds_read_b128 v[216:219], v170 offset:34816
	ds_read_b128 v[220:223], v170 offset:35840
	ds_read_b128 v[224:227], v170 offset:36864
	ds_read_b128 v[228:231], v170 offset:37888
	ds_read_b128 v[232:235], v170 offset:38912
	ds_read_b128 v[236:239], v170 offset:39936
	global_load_lds_dwordx4 v[242:243], off
	v_lshl_add_u64 v[242:243], s[24:25], 0, v[132:133]
	s_mov_b32 m0, s17
	s_nop 0
	global_load_lds_dwordx4 v[242:243], off
	s_waitcnt vmcnt(8)
	s_waitcnt lgkmcnt(0)
	s_barrier
	s_setprio 1
	s_waitcnt lgkmcnt(0)
	v_mfma_f32_16x16x32_bf16 v[124:127], v[146:149], v[208:211], v[124:127]
	v_mfma_f32_16x16x32_bf16 v[120:123], v[178:181], v[208:211], v[120:123]
	v_mfma_f32_16x16x32_bf16 v[108:111], v[146:149], v[216:219], v[108:111]
	v_mfma_f32_16x16x32_bf16 v[104:107], v[178:181], v[216:219], v[104:107]
	v_mfma_f32_16x16x32_bf16 v[92:95], v[146:149], v[224:227], v[92:95]
	v_mfma_f32_16x16x32_bf16 v[88:91], v[178:181], v[224:227], v[88:91]
	v_mfma_f32_16x16x32_bf16 v[76:79], v[146:149], v[232:235], v[76:79]
	v_mfma_f32_16x16x32_bf16 v[72:75], v[178:181], v[232:235], v[72:75]
	v_mfma_f32_16x16x32_bf16 v[124:127], v[172:175], v[212:215], v[124:127]
	v_mfma_f32_16x16x32_bf16 v[120:123], v[182:185], v[212:215], v[120:123]
	v_mfma_f32_16x16x32_bf16 v[108:111], v[172:175], v[220:223], v[108:111]
	v_mfma_f32_16x16x32_bf16 v[104:107], v[182:185], v[220:223], v[104:107]
	v_mfma_f32_16x16x32_bf16 v[92:95], v[172:175], v[228:231], v[92:95]
	v_mfma_f32_16x16x32_bf16 v[88:91], v[182:185], v[228:231], v[88:91]
	v_mfma_f32_16x16x32_bf16 v[76:79], v[172:175], v[236:239], v[76:79]
	v_mfma_f32_16x16x32_bf16 v[72:75], v[182:185], v[236:239], v[72:75]
	s_setprio 0
	s_setprio 1
	v_mfma_f32_16x16x32_bf16 v[116:119], v[186:189], v[208:211], v[116:119]
	v_mfma_f32_16x16x32_bf16 v[112:115], v[200:203], v[208:211], v[112:115]
	v_mfma_f32_16x16x32_bf16 v[100:103], v[186:189], v[216:219], v[100:103]
	v_mfma_f32_16x16x32_bf16 v[96:99], v[200:203], v[216:219], v[96:99]
	v_mfma_f32_16x16x32_bf16 v[84:87], v[186:189], v[224:227], v[84:87]
	v_mfma_f32_16x16x32_bf16 v[80:83], v[200:203], v[224:227], v[80:83]
	v_mfma_f32_16x16x32_bf16 v[68:71], v[186:189], v[232:235], v[68:71]
	v_mfma_f32_16x16x32_bf16 v[64:67], v[200:203], v[232:235], v[64:67]
	v_mfma_f32_16x16x32_bf16 v[116:119], v[190:193], v[212:215], v[116:119]
	v_mfma_f32_16x16x32_bf16 v[112:115], v[204:207], v[212:215], v[112:115]
	v_mfma_f32_16x16x32_bf16 v[100:103], v[190:193], v[220:223], v[100:103]
	v_mfma_f32_16x16x32_bf16 v[96:99], v[204:207], v[220:223], v[96:99]
	v_mfma_f32_16x16x32_bf16 v[84:87], v[190:193], v[228:231], v[84:87]
	v_mfma_f32_16x16x32_bf16 v[80:83], v[204:207], v[228:231], v[80:83]
	v_mfma_f32_16x16x32_bf16 v[68:71], v[190:193], v[236:239], v[68:71]
	v_mfma_f32_16x16x32_bf16 v[64:67], v[204:207], v[236:239], v[64:67]
	s_setprio 0
	s_barrier
; #define PG8_STAGE(bufoff, gbase, voff) do { _Pragma("unroll") for (int _i = 0; _i < 2; ++_i) \
;         __builtin_amdgcn_global_load_lds((const unsigned*)((const char*)(gbase) + (voff)[_i]), (LAS unsigned*)(lds + (bufoff) + ldsw + _i * 8192), 16, 0, 0); } while (0)
; #define PG8_LDA(dst, b, h) do { _Pragma("unroll") for (int m = 0; m < 4; ++m) _Pragma("unroll") for (int k = 0; k < 2; ++k) dst[m][k] = *(const LAS bf16x8*)(lds + PG8_SA(b, h) + aoff + m * 2048 + k * 1024); } while (0)
; #define PG8_LDB(dst, b, h) do { _Pragma("unroll") for (int n = 0; n < 2; ++n) _Pragma("unroll") for (int k = 0; k < 2; ++k) dst[n][k] = *(const LAS bf16x8*)(lds + PG8_SB(b, h) + boff + n * 2048 + k * 1024); } while (0)
; #define PG8_MMA(ai, bj, At, Bt) do { __builtin_amdgcn_s_setprio(1); _Pragma("unroll") for (int m = 0; m < 4; ++m) _Pragma("unroll") for (int n = 0; n < 2; ++n) _Pragma("unroll") for (int k = 0; k < 2; ++k) \
;         acc[ai][bj][m][n] = __builtin_amdgcn_mfma_f32_16x16x32_bf16(Bt[n][k], At[m][k], acc[ai][bj][m][n], 0, 0, 0); __builtin_amdgcn_s_setprio(0); } while (0)
; #define PG8_WAIT_V(n) asm volatile("s_waitcnt vmcnt(" #n ")" ::: "memory")
; #define PG8_WAIT_L(n) asm volatile("s_waitcnt lgkmcnt(" #n ")" ::: "memory")
; #define PG8_BAR __builtin_amdgcn_s_barrier()
; #define PG8_SCHED __builtin_amdgcn_sched_barrier(0)
; template <class Epi, int K, int lda, class Sched = StaticOrder, bool ALIGN_EPI = true>
; __device__ __forceinline__ void gemm_phase(LAS unsigned char* lds, const Gemm g, const Sched& S, const Epi& E) {
;     ...
;             PG8_LDB(B0, 1, 0); PG8_LDB(B1, 1, 1); PG8_SCHED; PG8_LDA(At, 1, 0); PG8_STAGE(PG8_SA(0, 1), a2 + hstepA, voffA);
;             PG8_WAIT_V(8); PG8_WAIT_L(0); PG8_BAR; PG8_MMA(0, 0, At, B0); PG8_MMA(0, 1, At, B1); PG8_BAR; PG8_SCHED;
;             PG8_LDA(At, 1, 1); PG8_STAGE(PG8_SB(1, 0), b3, voffB); PG8_STAGE(PG8_SB(1, 1), b3 + hstepB, voffB); PG8_STAGE(PG8_SA(1, 0), a3, voffA);
;             PG8_WAIT_V(8); PG8_WAIT_L(0); PG8_BAR; PG8_MMA(1, 0, At, B0); PG8_MMA(1, 1, At, B1); PG8_BAR; PG8_SCHED;
;         }
	s_add_i32 s23, s23, s87
	v_lshl_add_u64 v[150:151], v[150:151], 0, s[66:67]
	s_mov_b32 m0, s23
	ds_read_b128 v[208:211], v170 offset:49152
	ds_read_b128 v[212:215], v170 offset:50176
	ds_read_b128 v[216:219], v170 offset:51200
	ds_read_b128 v[220:223], v170 offset:52224
	ds_read_b128 v[224:227], v170 offset:53248
	ds_read_b128 v[228:231], v170 offset:54272
	ds_read_b128 v[232:235], v170 offset:55296
	ds_read_b128 v[236:239], v170 offset:56320
	global_load_lds_dwordx4 v[150:151], off
	s_add_i32 m0, s23, 0x2000
	s_add_u32 s24, s82, 0x100080
	v_lshl_add_u64 v[150:151], v[194:195], 0, s[66:67]
	s_addc_u32 s25, s83, 0
	s_add_i32 s23, s26, s87
	global_load_lds_dwordx4 v[150:151], off
	v_lshl_add_u64 v[150:151], s[24:25], 0, v[130:131]
	s_mov_b32 m0, s23
	s_nop 0
	global_load_lds_dwordx4 v[150:151], off
	v_lshl_add_u64 v[150:151], s[24:25], 0, v[134:135]
	s_add_i32 m0, s23, 0x2000
	s_nop 0
	global_load_lds_dwordx4 v[150:151], off
	v_lshl_add_u64 v[150:151], v[196:197], 0, s[66:67]
	s_mov_b32 m0, s18
	s_nop 0
	global_load_lds_dwordx4 v[150:151], off
	v_lshl_add_u64 v[150:151], v[240:241], 0, s[66:67]
	s_mov_b32 m0, s19
	s_nop 0
	global_load_lds_dwordx4 v[150:151], off
	s_waitcnt vmcnt(8)
	s_waitcnt lgkmcnt(0)
	s_barrier
	s_setprio 1
	s_waitcnt lgkmcnt(0)
	v_mfma_f32_16x16x32_bf16 v[60:63], v[146:149], v[208:211], v[60:63]
	v_mfma_f32_16x16x32_bf16 v[56:59], v[178:181], v[208:211], v[56:59]
	v_mfma_f32_16x16x32_bf16 v[44:47], v[146:149], v[216:219], v[44:47]
	v_mfma_f32_16x16x32_bf16 v[40:43], v[178:181], v[216:219], v[40:43]
	v_mfma_f32_16x16x32_bf16 v[28:31], v[146:149], v[224:227], v[28:31]
	v_mfma_f32_16x16x32_bf16 v[24:27], v[178:181], v[224:227], v[24:27]
	v_mfma_f32_16x16x32_bf16 v[12:15], v[146:149], v[232:235], v[12:15]
	v_mfma_f32_16x16x32_bf16 v[8:11], v[178:181], v[232:235], v[8:11]
	v_mfma_f32_16x16x32_bf16 v[60:63], v[172:175], v[212:215], v[60:63]
	v_mfma_f32_16x16x32_bf16 v[56:59], v[182:185], v[212:215], v[56:59]
	v_mfma_f32_16x16x32_bf16 v[44:47], v[172:175], v[220:223], v[44:47]
	v_mfma_f32_16x16x32_bf16 v[40:43], v[182:185], v[220:223], v[40:43]
	v_mfma_f32_16x16x32_bf16 v[28:31], v[172:175], v[228:231], v[28:31]
	v_mfma_f32_16x16x32_bf16 v[24:27], v[182:185], v[228:231], v[24:27]
	v_mfma_f32_16x16x32_bf16 v[12:15], v[172:175], v[236:239], v[12:15]
	v_mfma_f32_16x16x32_bf16 v[8:11], v[182:185], v[236:239], v[8:11]
	s_setprio 0
	s_setprio 1
	v_mfma_f32_16x16x32_bf16 v[52:55], v[186:189], v[208:211], v[52:55]
	v_mfma_f32_16x16x32_bf16 v[48:51], v[200:203], v[208:211], v[48:51]
	v_mfma_f32_16x16x32_bf16 v[36:39], v[186:189], v[216:219], v[36:39]
	v_mfma_f32_16x16x32_bf16 v[32:35], v[200:203], v[216:219], v[32:35]
	v_mfma_f32_16x16x32_bf16 v[20:23], v[186:189], v[224:227], v[20:23]
	v_mfma_f32_16x16x32_bf16 v[16:19], v[200:203], v[224:227], v[16:19]
	v_mfma_f32_16x16x32_bf16 v[4:7], v[186:189], v[232:235], v[4:7]
	v_mfma_f32_16x16x32_bf16 v[0:3], v[200:203], v[232:235], v[0:3]
	v_mfma_f32_16x16x32_bf16 v[52:55], v[190:193], v[212:215], v[52:55]
	v_mfma_f32_16x16x32_bf16 v[48:51], v[204:207], v[212:215], v[48:51]
	v_mfma_f32_16x16x32_bf16 v[36:39], v[190:193], v[220:223], v[36:39]
	v_mfma_f32_16x16x32_bf16 v[32:35], v[204:207], v[220:223], v[32:35]
	v_mfma_f32_16x16x32_bf16 v[20:23], v[190:193], v[228:231], v[20:23]
	v_mfma_f32_16x16x32_bf16 v[16:19], v[204:207], v[228:231], v[16:19]
	v_mfma_f32_16x16x32_bf16 v[4:7], v[190:193], v[236:239], v[4:7]
	v_mfma_f32_16x16x32_bf16 v[0:3], v[204:207], v[236:239], v[0:3]
	s_setprio 0
	s_add_i32 s22, s22, 2
	s_add_u32 s78, s78, 0x100
	s_addc_u32 s79, s79, 0
	s_cmp_gt_u32 s22, 61
	s_mov_b64 s[40:41], s[80:81]
	s_barrier
	s_cbranch_scc0 .LBB0_366
	s_and_b64 vcc, exec, s[74:75]
	s_cbranch_vccz .LBB0_369
	s_barrier

; #define PG8_STAGE(bufoff, gbase, voff) do { _Pragma("unroll") for (int _i = 0; _i < 2; ++_i) \
;         __builtin_amdgcn_global_load_lds((const unsigned*)((const char*)(gbase) + (voff)[_i]), (LAS unsigned*)(lds + (bufoff) + ldsw + _i * 8192), 16, 0, 0); } while (0)
; #define PG8_LDA(dst, b, h) do { _Pragma("unroll") for (int m = 0; m < 4; ++m) _Pragma("unroll") for (int k = 0; k < 2; ++k) dst[m][k] = *(const LAS bf16x8*)(lds + PG8_SA(b, h) + aoff + m * 2048 + k * 1024); } while (0)
; #define PG8_LDB(dst, b, h) do { _Pragma("unroll") for (int n = 0; n < 2; ++n) _Pragma("unroll") for (int k = 0; k < 2; ++k) dst[n][k] = *(const LAS bf16x8*)(lds + PG8_SB(b, h) + boff + n * 2048 + k * 1024); } while (0)
; #define PG8_MMA(ai, bj, At, Bt) do { __builtin_amdgcn_s_setprio(1); _Pragma("unroll") for (int m = 0; m < 4; ++m) _Pragma("unroll") for (int n = 0; n < 2; ++n) _Pragma("unroll") for (int k = 0; k < 2; ++k) \
;         acc[ai][bj][m][n] = __builtin_amdgcn_mfma_f32_16x16x32_bf16(Bt[n][k], At[m][k], acc[ai][bj][m][n], 0, 0, 0); __builtin_amdgcn_s_setprio(0); } while (0)
; #define PG8_WAIT_V(n) asm volatile("s_waitcnt vmcnt(" #n ")" ::: "memory")
; #define PG8_WAIT_L(n) asm volatile("s_waitcnt lgkmcnt(" #n ")" ::: "memory")
; #define PG8_BAR __builtin_amdgcn_s_barrier()
; template <class Epi, int K, int lda, class Sched = StaticOrder, bool ALIGN_EPI = true>
; __device__ __forceinline__ void gemm_phase(LAS unsigned char* lds, const Gemm g, const Sched& S, const Epi& E) {
;     ...
;         for (int t = 0; t < nt; t += 2) {
;             const bool last = (t == nt - 2);
;             const char* a1 = cA + (size_t)(t + 1) * kstep;
;             const char* a2 = last ? nA : cA + (size_t)(t + 2) * kstep; const char* b2 = last ? nB : cB + (size_t)(t + 2) * kstep;
;             const char* a3 = a2 + kstep; const char* b3 = b2 + kstep;
;             PG8_LDB(B0, 0, 0); PG8_LDB(B1, 0, 1); PG8_SCHED; PG8_LDA(At, 0, 0); PG8_STAGE(PG8_SA(1, 1), a1 + hstepA, voffA);
;             PG8_WAIT_V(8); PG8_WAIT_L(0); PG8_BAR; PG8_MMA(0, 0, At, B0); PG8_MMA(0, 1, At, B1); PG8_BAR; PG8_SCHED;
;             PG8_LDA(At, 0, 1); PG8_STAGE(PG8_SB(0, 0), b2, voffB); PG8_STAGE(PG8_SB(0, 1), b2 + hstepB, voffB); PG8_STAGE(PG8_SA(0, 0), a2, voffA);
;             PG8_WAIT_V(8); PG8_WAIT_L(0); PG8_BAR; PG8_MMA(1, 0, At, B0); PG8_MMA(1, 1, At, B1); PG8_BAR; PG8_SCHED;
.LBB0_474:
	s_add_u32 s22, s38, 0xfff80080
	s_addc_u32 s23, s39, -1
	s_add_i32 s24, 0, 0x10000
	s_cmp_eq_u32 s21, 28
	s_cselect_b32 s79, s19, s23
	s_cselect_b32 s78, s20, s22
	v_add_u32_e32 v160, s24, v170
	s_cselect_b32 s77, s41, s75
	s_cselect_b32 s76, s40, s74
	s_add_i32 s25, 0, 0x14000
	ds_read_b128 v[156:159], v160
	ds_read_b128 v[182:185], v160 offset:1024
	ds_read_b128 v[186:189], v160 offset:2048
	ds_read_b128 v[190:193], v160 offset:3072
	v_add_u32_e32 v160, s25, v170
	ds_read_b128 v[200:203], v160
	ds_read_b128 v[204:207], v160 offset:1024
	ds_read_b128 v[208:211], v160 offset:2048
	ds_read_b128 v[212:215], v160 offset:3072
	v_lshl_add_u64 v[160:161], s[38:39], 0, v[152:153]
	s_add_i32 m0, s14, 0xc000
	ds_read_b128 v[216:219], v179
	ds_read_b128 v[220:223], v179 offset:1024
	ds_read_b128 v[224:227], v179 offset:2048
	ds_read_b128 v[228:231], v179 offset:3072
	ds_read_b128 v[232:235], v179 offset:4096
	ds_read_b128 v[236:239], v179 offset:5120
	ds_read_b128 v[240:243], v179 offset:6144
	ds_read_b128 v[244:247], v179 offset:7168
	global_load_lds_dwordx4 v[160:161], off
	v_lshl_add_u64 v[160:161], s[38:39], 0, v[154:155]
	s_add_i32 m0, s14, 0xe000
	s_nop 0
	global_load_lds_dwordx4 v[160:161], off
	s_waitcnt vmcnt(8)
	s_waitcnt lgkmcnt(0)
	s_barrier
	s_setprio 1
	s_waitcnt lgkmcnt(0)
	v_mfma_f32_16x16x32_bf16 v[124:127], v[156:159], v[216:219], v[124:127]
	v_mfma_f32_16x16x32_bf16 v[120:123], v[186:189], v[216:219], v[120:123]
	v_mfma_f32_16x16x32_bf16 v[108:111], v[156:159], v[224:227], v[108:111]
	v_mfma_f32_16x16x32_bf16 v[104:107], v[186:189], v[224:227], v[104:107]
	v_mfma_f32_16x16x32_bf16 v[92:95], v[156:159], v[232:235], v[92:95]
	v_mfma_f32_16x16x32_bf16 v[88:91], v[186:189], v[232:235], v[88:91]
	v_mfma_f32_16x16x32_bf16 v[76:79], v[156:159], v[240:243], v[76:79]
	v_mfma_f32_16x16x32_bf16 v[72:75], v[186:189], v[240:243], v[72:75]
	v_mfma_f32_16x16x32_bf16 v[124:127], v[182:185], v[220:223], v[124:127]
	v_mfma_f32_16x16x32_bf16 v[120:123], v[190:193], v[220:223], v[120:123]
	v_mfma_f32_16x16x32_bf16 v[108:111], v[182:185], v[228:231], v[108:111]
	v_mfma_f32_16x16x32_bf16 v[104:107], v[190:193], v[228:231], v[104:107]
	v_mfma_f32_16x16x32_bf16 v[92:95], v[182:185], v[236:239], v[92:95]
	v_mfma_f32_16x16x32_bf16 v[88:91], v[190:193], v[236:239], v[88:91]
	v_mfma_f32_16x16x32_bf16 v[76:79], v[182:185], v[244:247], v[76:79]
	v_mfma_f32_16x16x32_bf16 v[72:75], v[190:193], v[244:247], v[72:75]
	s_setprio 0
	s_setprio 1
	v_mfma_f32_16x16x32_bf16 v[116:119], v[200:203], v[216:219], v[116:119]
	v_mfma_f32_16x16x32_bf16 v[112:115], v[208:211], v[216:219], v[112:115]
	v_mfma_f32_16x16x32_bf16 v[100:103], v[200:203], v[224:227], v[100:103]
	v_mfma_f32_16x16x32_bf16 v[96:99], v[208:211], v[224:227], v[96:99]
	v_mfma_f32_16x16x32_bf16 v[84:87], v[200:203], v[232:235], v[84:87]
	v_mfma_f32_16x16x32_bf16 v[80:83], v[208:211], v[232:235], v[80:83]
	v_mfma_f32_16x16x32_bf16 v[68:71], v[200:203], v[240:243], v[68:71]
	v_mfma_f32_16x16x32_bf16 v[64:67], v[208:211], v[240:243], v[64:67]
	v_mfma_f32_16x16x32_bf16 v[116:119], v[204:207], v[220:223], v[116:119]
	v_mfma_f32_16x16x32_bf16 v[112:115], v[212:215], v[220:223], v[112:115]
	v_mfma_f32_16x16x32_bf16 v[100:103], v[204:207], v[228:231], v[100:103]
	v_mfma_f32_16x16x32_bf16 v[96:99], v[212:215], v[228:231], v[96:99]
	v_mfma_f32_16x16x32_bf16 v[84:87], v[204:207], v[236:239], v[84:87]
	v_mfma_f32_16x16x32_bf16 v[80:83], v[212:215], v[236:239], v[80:83]
	v_mfma_f32_16x16x32_bf16 v[68:71], v[204:207], v[244:247], v[68:71]
	v_mfma_f32_16x16x32_bf16 v[64:67], v[212:215], v[244:247], v[64:67]
	s_setprio 0
	s_barrier
	s_add_i32 s22, s24, s80
	v_lshl_add_u64 v[160:161], s[76:77], 0, v[176:177]
	s_mov_b32 m0, s22
	ds_read_b128 v[216:219], v179 offset:16384
	ds_read_b128 v[220:223], v179 offset:17408
	ds_read_b128 v[224:227], v179 offset:18432
	ds_read_b128 v[228:231], v179 offset:19456
	ds_read_b128 v[232:235], v179 offset:20480
	ds_read_b128 v[236:239], v179 offset:21504
	ds_read_b128 v[240:243], v179 offset:22528
	ds_read_b128 v[244:247], v179 offset:23552
	global_load_lds_dwordx4 v[160:161], off
	s_add_i32 m0, s22, 0x2000
	s_add_u32 s22, s76, 0x80000
	v_lshl_add_u64 v[248:249], s[76:77], 0, v[128:129]
	s_addc_u32 s23, s77, 0
	s_add_i32 s24, s25, s80
	global_load_lds_dwordx4 v[248:249], off
	v_lshl_add_u64 v[250:251], s[22:23], 0, v[176:177]
	s_mov_b32 m0, s24
	v_lshl_add_u64 v[196:197], s[78:79], 0, v[128:129]
	global_load_lds_dwordx4 v[250:251], off
	v_lshl_add_u64 v[250:251], s[22:23], 0, v[128:129]
	s_add_i32 m0, s24, 0x2000
	s_nop 0
	global_load_lds_dwordx4 v[250:251], off
	v_lshl_add_u64 v[250:251], s[78:79], 0, v[176:177]
	s_mov_b32 m0, s14
	s_nop 0
	global_load_lds_dwordx4 v[250:251], off
	s_mov_b32 m0, s15
	s_nop 0
	global_load_lds_dwordx4 v[196:197], off
	s_waitcnt vmcnt(8)
	s_waitcnt lgkmcnt(0)
	s_barrier
; #define PG8_STAGE(bufoff, gbase, voff) do { _Pragma("unroll") for (int _i = 0; _i < 2; ++_i) \
;         __builtin_amdgcn_global_load_lds((const unsigned*)((const char*)(gbase) + (voff)[_i]), (LAS unsigned*)(lds + (bufoff) + ldsw + _i * 8192), 16, 0, 0); } while (0)
; #define PG8_LDA(dst, b, h) do { _Pragma("unroll") for (int m = 0; m < 4; ++m) _Pragma("unroll") for (int k = 0; k < 2; ++k) dst[m][k] = *(const LAS bf16x8*)(lds + PG8_SA(b, h) + aoff + m * 2048 + k * 1024); } while (0)
; #define PG8_LDB(dst, b, h) do { _Pragma("unroll") for (int n = 0; n < 2; ++n) _Pragma("unroll") for (int k = 0; k < 2; ++k) dst[n][k] = *(const LAS bf16x8*)(lds + PG8_SB(b, h) + boff + n * 2048 + k * 1024); } while (0)
; #define PG8_MMA(ai, bj, At, Bt) do { __builtin_amdgcn_s_setprio(1); _Pragma("unroll") for (int m = 0; m < 4; ++m) _Pragma("unroll") for (int n = 0; n < 2; ++n) _Pragma("unroll") for (int k = 0; k < 2; ++k) \
;         acc[ai][bj][m][n] = __builtin_amdgcn_mfma_f32_16x16x32_bf16(Bt[n][k], At[m][k], acc[ai][bj][m][n], 0, 0, 0); __builtin_amdgcn_s_setprio(0); } while (0)
; #define PG8_WAIT_V(n) asm volatile("s_waitcnt vmcnt(" #n ")" ::: "memory")
; #define PG8_WAIT_L(n) asm volatile("s_waitcnt lgkmcnt(" #n ")" ::: "memory")
; #define PG8_BAR __builtin_amdgcn_s_barrier()
; #define PG8_SCHED __builtin_amdgcn_sched_barrier(0)
; template <class Epi, int K, int lda, class Sched = StaticOrder, bool ALIGN_EPI = true>
; __device__ __forceinline__ void gemm_phase(LAS unsigned char* lds, const Gemm g, const Sched& S, const Epi& E) {
;     ...
;             PG8_WAIT_V(8); PG8_WAIT_L(0); PG8_BAR; PG8_MMA(0, 0, At, B0); PG8_MMA(0, 1, At, B1); PG8_BAR; PG8_SCHED;
;             PG8_LDA(At, 0, 1); PG8_STAGE(PG8_SB(0, 0), b2, voffB); PG8_STAGE(PG8_SB(0, 1), b2 + hstepB, voffB); PG8_STAGE(PG8_SA(0, 0), a2, voffA);
;             PG8_WAIT_V(8); PG8_WAIT_L(0); PG8_BAR; PG8_MMA(1, 0, At, B0); PG8_MMA(1, 1, At, B1); PG8_BAR; PG8_SCHED;
;             PG8_LDB(B0, 1, 0); PG8_LDB(B1, 1, 1); PG8_SCHED; PG8_LDA(At, 1, 0); PG8_STAGE(PG8_SA(0, 1), a2 + hstepA, voffA);
;             PG8_WAIT_V(8); PG8_WAIT_L(0); PG8_BAR; PG8_MMA(0, 0, At, B0); PG8_MMA(0, 1, At, B1); PG8_BAR; PG8_SCHED;
	s_setprio 1
	s_waitcnt lgkmcnt(0)
	v_mfma_f32_16x16x32_bf16 v[60:63], v[156:159], v[216:219], v[60:63]
	v_mfma_f32_16x16x32_bf16 v[56:59], v[186:189], v[216:219], v[56:59]
	v_mfma_f32_16x16x32_bf16 v[44:47], v[156:159], v[224:227], v[44:47]
	v_mfma_f32_16x16x32_bf16 v[40:43], v[186:189], v[224:227], v[40:43]
	v_mfma_f32_16x16x32_bf16 v[28:31], v[156:159], v[232:235], v[28:31]
	v_mfma_f32_16x16x32_bf16 v[24:27], v[186:189], v[232:235], v[24:27]
	v_mfma_f32_16x16x32_bf16 v[12:15], v[156:159], v[240:243], v[12:15]
	v_mfma_f32_16x16x32_bf16 v[8:11], v[186:189], v[240:243], v[8:11]
	v_mfma_f32_16x16x32_bf16 v[60:63], v[182:185], v[220:223], v[60:63]
	v_mfma_f32_16x16x32_bf16 v[56:59], v[190:193], v[220:223], v[56:59]
	v_mfma_f32_16x16x32_bf16 v[44:47], v[182:185], v[228:231], v[44:47]
	v_mfma_f32_16x16x32_bf16 v[40:43], v[190:193], v[228:231], v[40:43]
	v_mfma_f32_16x16x32_bf16 v[28:31], v[182:185], v[236:239], v[28:31]
	v_mfma_f32_16x16x32_bf16 v[24:27], v[190:193], v[236:239], v[24:27]
	v_mfma_f32_16x16x32_bf16 v[12:15], v[182:185], v[244:247], v[12:15]
	v_mfma_f32_16x16x32_bf16 v[8:11], v[190:193], v[244:247], v[8:11]
	s_setprio 0
	s_setprio 1
	v_mfma_f32_16x16x32_bf16 v[52:55], v[200:203], v[216:219], v[52:55]
	v_mfma_f32_16x16x32_bf16 v[48:51], v[208:211], v[216:219], v[48:51]
	v_mfma_f32_16x16x32_bf16 v[36:39], v[200:203], v[224:227], v[36:39]
	v_mfma_f32_16x16x32_bf16 v[32:35], v[208:211], v[224:227], v[32:35]
	v_mfma_f32_16x16x32_bf16 v[20:23], v[200:203], v[232:235], v[20:23]
	v_mfma_f32_16x16x32_bf16 v[16:19], v[208:211], v[232:235], v[16:19]
	v_mfma_f32_16x16x32_bf16 v[4:7], v[200:203], v[240:243], v[4:7]
	v_mfma_f32_16x16x32_bf16 v[0:3], v[208:211], v[240:243], v[0:3]
	v_mfma_f32_16x16x32_bf16 v[52:55], v[204:207], v[220:223], v[52:55]
	v_mfma_f32_16x16x32_bf16 v[48:51], v[212:215], v[220:223], v[48:51]
	v_mfma_f32_16x16x32_bf16 v[36:39], v[204:207], v[228:231], v[36:39]
	v_mfma_f32_16x16x32_bf16 v[32:35], v[212:215], v[228:231], v[32:35]
	v_mfma_f32_16x16x32_bf16 v[20:23], v[204:207], v[236:239], v[20:23]
	v_mfma_f32_16x16x32_bf16 v[16:19], v[212:215], v[236:239], v[16:19]
	v_mfma_f32_16x16x32_bf16 v[4:7], v[204:207], v[244:247], v[4:7]
	v_mfma_f32_16x16x32_bf16 v[0:3], v[212:215], v[244:247], v[0:3]
	s_setprio 0
	s_barrier
	s_add_i32 s24, 0, 0x18000
	v_add_u32_e32 v181, s24, v170
	s_add_i32 s25, 0, 0x1c000
	ds_read_b128 v[156:159], v181
	ds_read_b128 v[182:185], v181 offset:1024
	ds_read_b128 v[186:189], v181 offset:2048
	ds_read_b128 v[190:193], v181 offset:3072
	v_add_u32_e32 v181, s25, v170
	ds_read_b128 v[200:203], v181
	ds_read_b128 v[204:207], v181 offset:1024
	ds_read_b128 v[208:211], v181 offset:2048
	ds_read_b128 v[212:215], v181 offset:3072
	s_add_u32 s22, s78, 0x80000
	s_addc_u32 s23, s79, 0
	s_mov_b32 m0, s16
	v_lshl_add_u64 v[194:195], s[22:23], 0, v[176:177]
	ds_read_b128 v[216:219], v179 offset:32768
	ds_read_b128 v[220:223], v179 offset:33792
	ds_read_b128 v[224:227], v179 offset:34816
	ds_read_b128 v[228:231], v179 offset:35840
	ds_read_b128 v[232:235], v179 offset:36864
	ds_read_b128 v[236:239], v179 offset:37888
	ds_read_b128 v[240:243], v179 offset:38912
	ds_read_b128 v[244:247], v179 offset:39936
	global_load_lds_dwordx4 v[194:195], off
	v_lshl_add_u64 v[194:195], s[22:23], 0, v[128:129]
	s_mov_b32 m0, s17
	s_nop 0
	global_load_lds_dwordx4 v[194:195], off
	s_waitcnt vmcnt(8)
	s_waitcnt lgkmcnt(0)
	s_barrier
	s_setprio 1
	s_waitcnt lgkmcnt(0)
	v_mfma_f32_16x16x32_bf16 v[124:127], v[156:159], v[216:219], v[124:127]
	v_mfma_f32_16x16x32_bf16 v[120:123], v[186:189], v[216:219], v[120:123]
	v_mfma_f32_16x16x32_bf16 v[108:111], v[156:159], v[224:227], v[108:111]
	v_mfma_f32_16x16x32_bf16 v[104:107], v[186:189], v[224:227], v[104:107]
	v_mfma_f32_16x16x32_bf16 v[92:95], v[156:159], v[232:235], v[92:95]
	v_mfma_f32_16x16x32_bf16 v[88:91], v[186:189], v[232:235], v[88:91]
	v_mfma_f32_16x16x32_bf16 v[76:79], v[156:159], v[240:243], v[76:79]
	v_mfma_f32_16x16x32_bf16 v[72:75], v[186:189], v[240:243], v[72:75]
	v_mfma_f32_16x16x32_bf16 v[124:127], v[182:185], v[220:223], v[124:127]
	v_mfma_f32_16x16x32_bf16 v[120:123], v[190:193], v[220:223], v[120:123]
	v_mfma_f32_16x16x32_bf16 v[108:111], v[182:185], v[228:231], v[108:111]
	v_mfma_f32_16x16x32_bf16 v[104:107], v[190:193], v[228:231], v[104:107]
	v_mfma_f32_16x16x32_bf16 v[92:95], v[182:185], v[236:239], v[92:95]
	v_mfma_f32_16x16x32_bf16 v[88:91], v[190:193], v[236:239], v[88:91]
	v_mfma_f32_16x16x32_bf16 v[76:79], v[182:185], v[244:247], v[76:79]
	v_mfma_f32_16x16x32_bf16 v[72:75], v[190:193], v[244:247], v[72:75]
	s_setprio 0
	s_setprio 1
	v_mfma_f32_16x16x32_bf16 v[116:119], v[200:203], v[216:219], v[116:119]
	v_mfma_f32_16x16x32_bf16 v[112:115], v[208:211], v[216:219], v[112:115]
	v_mfma_f32_16x16x32_bf16 v[100:103], v[200:203], v[224:227], v[100:103]
	v_mfma_f32_16x16x32_bf16 v[96:99], v[208:211], v[224:227], v[96:99]
	v_mfma_f32_16x16x32_bf16 v[84:87], v[200:203], v[232:235], v[84:87]
	v_mfma_f32_16x16x32_bf16 v[80:83], v[208:211], v[232:235], v[80:83]
	v_mfma_f32_16x16x32_bf16 v[68:71], v[200:203], v[240:243], v[68:71]
	v_mfma_f32_16x16x32_bf16 v[64:67], v[208:211], v[240:243], v[64:67]
	v_mfma_f32_16x16x32_bf16 v[116:119], v[204:207], v[220:223], v[116:119]
	v_mfma_f32_16x16x32_bf16 v[112:115], v[212:215], v[220:223], v[112:115]
	v_mfma_f32_16x16x32_bf16 v[100:103], v[204:207], v[228:231], v[100:103]
	v_mfma_f32_16x16x32_bf16 v[96:99], v[212:215], v[228:231], v[96:99]
	v_mfma_f32_16x16x32_bf16 v[84:87], v[204:207], v[236:239], v[84:87]
	v_mfma_f32_16x16x32_bf16 v[80:83], v[212:215], v[236:239], v[80:83]
	v_mfma_f32_16x16x32_bf16 v[68:71], v[204:207], v[244:247], v[68:71]
	v_mfma_f32_16x16x32_bf16 v[64:67], v[212:215], v[244:247], v[64:67]
	s_setprio 0
	s_barrier
; #define PG8_STAGE(bufoff, gbase, voff) do { _Pragma("unroll") for (int _i = 0; _i < 2; ++_i) \
;         __builtin_amdgcn_global_load_lds((const unsigned*)((const char*)(gbase) + (voff)[_i]), (LAS unsigned*)(lds + (bufoff) + ldsw + _i * 8192), 16, 0, 0); } while (0)
; #define PG8_LDA(dst, b, h) do { _Pragma("unroll") for (int m = 0; m < 4; ++m) _Pragma("unroll") for (int k = 0; k < 2; ++k) dst[m][k] = *(const LAS bf16x8*)(lds + PG8_SA(b, h) + aoff + m * 2048 + k * 1024); } while (0)
; #define PG8_LDB(dst, b, h) do { _Pragma("unroll") for (int n = 0; n < 2; ++n) _Pragma("unroll") for (int k = 0; k < 2; ++k) dst[n][k] = *(const LAS bf16x8*)(lds + PG8_SB(b, h) + boff + n * 2048 + k * 1024); } while (0)
; #define PG8_MMA(ai, bj, At, Bt) do { __builtin_amdgcn_s_setprio(1); _Pragma("unroll") for (int m = 0; m < 4; ++m) _Pragma("unroll") for (int n = 0; n < 2; ++n) _Pragma("unroll") for (int k = 0; k < 2; ++k) \
;         acc[ai][bj][m][n] = __builtin_amdgcn_mfma_f32_16x16x32_bf16(Bt[n][k], At[m][k], acc[ai][bj][m][n], 0, 0, 0); __builtin_amdgcn_s_setprio(0); } while (0)
; #define PG8_WAIT_V(n) asm volatile("s_waitcnt vmcnt(" #n ")" ::: "memory")
; #define PG8_WAIT_L(n) asm volatile("s_waitcnt lgkmcnt(" #n ")" ::: "memory")
; #define PG8_BAR __builtin_amdgcn_s_barrier()
; #define PG8_SCHED __builtin_amdgcn_sched_barrier(0)
; template <class Epi, int K, int lda, class Sched = StaticOrder, bool ALIGN_EPI = true>
; __device__ __forceinline__ void gemm_phase(LAS unsigned char* lds, const Gemm g, const Sched& S, const Epi& E) {
;     ...
;             PG8_LDB(B0, 1, 0); PG8_LDB(B1, 1, 1); PG8_SCHED; PG8_LDA(At, 1, 0); PG8_STAGE(PG8_SA(0, 1), a2 + hstepA, voffA);
;             PG8_WAIT_V(8); PG8_WAIT_L(0); PG8_BAR; PG8_MMA(0, 0, At, B0); PG8_MMA(0, 1, At, B1); PG8_BAR; PG8_SCHED;
;             PG8_LDA(At, 1, 1); PG8_STAGE(PG8_SB(1, 0), b3, voffB); PG8_STAGE(PG8_SB(1, 1), b3 + hstepB, voffB); PG8_STAGE(PG8_SA(1, 0), a3, voffA);
;             PG8_WAIT_V(8); PG8_WAIT_L(0); PG8_BAR; PG8_MMA(1, 0, At, B0); PG8_MMA(1, 1, At, B1); PG8_BAR; PG8_SCHED;
;         }
	s_add_i32 s22, s24, s80
	v_lshl_add_u64 v[160:161], v[160:161], 0, s[66:67]
	s_mov_b32 m0, s22
	ds_read_b128 v[216:219], v179 offset:49152
	ds_read_b128 v[220:223], v179 offset:50176
	ds_read_b128 v[224:227], v179 offset:51200
	ds_read_b128 v[228:231], v179 offset:52224
	ds_read_b128 v[232:235], v179 offset:53248
	ds_read_b128 v[236:239], v179 offset:54272
	ds_read_b128 v[240:243], v179 offset:55296
	ds_read_b128 v[244:247], v179 offset:56320
	global_load_lds_dwordx4 v[160:161], off
	s_add_i32 m0, s22, 0x2000
	s_add_u32 s22, s76, 0x80080
	v_lshl_add_u64 v[160:161], v[248:249], 0, s[66:67]
	s_addc_u32 s23, s77, 0
	s_add_i32 s24, s25, s80
	global_load_lds_dwordx4 v[160:161], off
	v_lshl_add_u64 v[160:161], s[22:23], 0, v[176:177]
	s_mov_b32 m0, s24
	s_nop 0
	global_load_lds_dwordx4 v[160:161], off
	v_lshl_add_u64 v[160:161], s[22:23], 0, v[128:129]
	s_add_i32 m0, s24, 0x2000
	s_nop 0
	global_load_lds_dwordx4 v[160:161], off
	v_lshl_add_u64 v[160:161], v[250:251], 0, s[66:67]
	s_mov_b32 m0, s81
	s_nop 0
	global_load_lds_dwordx4 v[160:161], off
	v_lshl_add_u64 v[160:161], v[196:197], 0, s[66:67]
	s_mov_b32 m0, s82
	s_nop 0
	global_load_lds_dwordx4 v[160:161], off
	s_waitcnt vmcnt(8)
	s_waitcnt lgkmcnt(0)
	s_barrier
	s_setprio 1
	s_waitcnt lgkmcnt(0)
	v_mfma_f32_16x16x32_bf16 v[60:63], v[156:159], v[216:219], v[60:63]
	v_mfma_f32_16x16x32_bf16 v[56:59], v[186:189], v[216:219], v[56:59]
	v_mfma_f32_16x16x32_bf16 v[44:47], v[156:159], v[224:227], v[44:47]
	v_mfma_f32_16x16x32_bf16 v[40:43], v[186:189], v[224:227], v[40:43]
	v_mfma_f32_16x16x32_bf16 v[28:31], v[156:159], v[232:235], v[28:31]
	v_mfma_f32_16x16x32_bf16 v[24:27], v[186:189], v[232:235], v[24:27]
	v_mfma_f32_16x16x32_bf16 v[12:15], v[156:159], v[240:243], v[12:15]
	v_mfma_f32_16x16x32_bf16 v[8:11], v[186:189], v[240:243], v[8:11]
	v_mfma_f32_16x16x32_bf16 v[60:63], v[182:185], v[220:223], v[60:63]
	v_mfma_f32_16x16x32_bf16 v[56:59], v[190:193], v[220:223], v[56:59]
	v_mfma_f32_16x16x32_bf16 v[44:47], v[182:185], v[228:231], v[44:47]
	v_mfma_f32_16x16x32_bf16 v[40:43], v[190:193], v[228:231], v[40:43]
	v_mfma_f32_16x16x32_bf16 v[28:31], v[182:185], v[236:239], v[28:31]
	v_mfma_f32_16x16x32_bf16 v[24:27], v[190:193], v[236:239], v[24:27]
	v_mfma_f32_16x16x32_bf16 v[12:15], v[182:185], v[244:247], v[12:15]
	v_mfma_f32_16x16x32_bf16 v[8:11], v[190:193], v[244:247], v[8:11]
	s_setprio 0
	s_setprio 1
	v_mfma_f32_16x16x32_bf16 v[52:55], v[200:203], v[216:219], v[52:55]
	v_mfma_f32_16x16x32_bf16 v[48:51], v[208:211], v[216:219], v[48:51]
	v_mfma_f32_16x16x32_bf16 v[36:39], v[200:203], v[224:227], v[36:39]
	v_mfma_f32_16x16x32_bf16 v[32:35], v[208:211], v[224:227], v[32:35]
	v_mfma_f32_16x16x32_bf16 v[20:23], v[200:203], v[232:235], v[20:23]
	v_mfma_f32_16x16x32_bf16 v[16:19], v[208:211], v[232:235], v[16:19]
	v_mfma_f32_16x16x32_bf16 v[4:7], v[200:203], v[240:243], v[4:7]
	v_mfma_f32_16x16x32_bf16 v[0:3], v[208:211], v[240:243], v[0:3]
	v_mfma_f32_16x16x32_bf16 v[52:55], v[204:207], v[220:223], v[52:55]
	v_mfma_f32_16x16x32_bf16 v[48:51], v[212:215], v[220:223], v[48:51]
	v_mfma_f32_16x16x32_bf16 v[36:39], v[204:207], v[228:231], v[36:39]
	v_mfma_f32_16x16x32_bf16 v[32:35], v[212:215], v[228:231], v[32:35]
	v_mfma_f32_16x16x32_bf16 v[20:23], v[204:207], v[236:239], v[20:23]
	v_mfma_f32_16x16x32_bf16 v[16:19], v[212:215], v[236:239], v[16:19]
	v_mfma_f32_16x16x32_bf16 v[4:7], v[204:207], v[244:247], v[4:7]
	v_mfma_f32_16x16x32_bf16 v[0:3], v[212:215], v[244:247], v[0:3]
	s_setprio 0
	s_add_i32 s21, s21, 2
	s_add_u32 s38, s38, 0x100
	s_addc_u32 s39, s39, 0
	s_add_u32 s74, s74, 0x100
	s_addc_u32 s75, s75, 0
	s_cmp_gt_u32 s21, 29
	s_barrier
	s_cbranch_scc0 .LBB0_474
	s_and_b64 vcc, exec, s[52:53]
	s_cbranch_vccz .LBB0_477
	s_barrier
